# attention main loop: loop bookkeeping rotated in front of the step barriers, two no-op adds removed; on top of DMA-in-gaps + QK-first
# baseline (speedup 1.0000x reference)
.LBB0_1062:
	s_mov_b32 s34, s18
	s_mov_b32 s1, s12
	v_mfma_f32_32x32x16_bf16 v[130:145], v[206:209], v[174:177], 0
	v_lshl_add_u32 v218, s4, 1, v240
	ds_read_b64_tr_b16 v[68:69], v218 offset:24576
	ds_read_b64_tr_b16 v[70:71], v218 offset:25088
	v_add_f32_e32 v67, v98, v99
	v_add_f32_e32 v67, v100, v67
	v_add_f32_e32 v67, v101, v67
	v_add_f32_e32 v67, v102, v67
	v_add_f32_e32 v67, v103, v67
	v_cvt_pk_bf16_f32 v162, v98, v99
	v_cvt_pk_bf16_f32 v163, v100, v101
	s_waitcnt lgkmcnt(9)
	ds_read_b64_tr_b16 v[72:73], v218 offset:28672
	ds_read_b64_tr_b16 v[74:75], v218 offset:29184
	v_add_f32_e32 v67, v104, v67
	v_add_f32_e32 v67, v105, v67
	v_add_f32_e32 v67, v106, v67
	v_add_f32_e32 v67, v107, v67
	v_cvt_pk_bf16_f32 v164, v102, v103
	v_cvt_pk_bf16_f32 v165, v104, v105
	s_waitcnt lgkmcnt(10)
	v_mfma_f32_32x32x16_bf16 v[114:129], v[202:205], v[174:177], 0
	ds_read_b64_tr_b16 v[76:77], v218 offset:25600
	ds_read_b64_tr_b16 v[78:79], v218 offset:26112
	v_add_f32_e32 v67, v108, v67
	v_add_f32_e32 v67, v109, v67
	v_add_f32_e32 v67, v110, v67
	v_add_f32_e32 v67, v111, v67
	v_cvt_pk_bf16_f32 v158, v106, v107
	v_cvt_pk_bf16_f32 v159, v108, v109
	s_waitcnt lgkmcnt(11)
	v_mfma_f32_32x32x16_bf16 v[130:145], v[198:201], v[170:173], v[130:145]
	ds_read_b64_tr_b16 v[98:99], v218 offset:29696
	ds_read_b64_tr_b16 v[100:101], v218 offset:30208
	v_add_f32_e32 v67, v112, v67
	v_add_f32_e32 v67, v113, v67
	v_add_f32_e32 v67, v82, v67
	v_add_f32_e32 v67, v83, v67
	v_cvt_pk_bf16_f32 v160, v110, v111
	v_cvt_pk_bf16_f32 v161, v112, v113
	s_waitcnt lgkmcnt(12)
	v_mfma_f32_32x32x16_bf16 v[114:129], v[194:197], v[170:173], v[114:129]
	ds_read_b64_tr_b16 v[102:103], v218 offset:26624
	ds_read_b64_tr_b16 v[104:105], v218 offset:27136
	v_add_f32_e32 v67, v84, v67
	v_add_f32_e32 v67, v85, v67
	v_add_f32_e32 v67, v86, v67
	v_add_f32_e32 v67, v87, v67
	v_cvt_pk_bf16_f32 v150, v82, v83
	v_cvt_pk_bf16_f32 v151, v84, v85
	s_waitcnt lgkmcnt(13)
	v_mfma_f32_32x32x16_bf16 v[130:145], v[190:193], v[166:169], v[130:145]
	ds_read_b64_tr_b16 v[106:107], v218 offset:30720
	ds_read_b64_tr_b16 v[108:109], v218 offset:31232
	v_add_f32_e32 v67, v88, v67
	v_add_f32_e32 v67, v89, v67
	v_add_f32_e32 v67, v90, v67
	v_add_f32_e32 v67, v91, v67
	v_cvt_pk_bf16_f32 v152, v86, v87
	v_cvt_pk_bf16_f32 v153, v88, v89
	s_waitcnt lgkmcnt(14)
	v_mfma_f32_32x32x16_bf16 v[114:129], v[186:189], v[166:169], v[114:129]
	ds_read_b64_tr_b16 v[110:111], v218 offset:27648
	ds_read_b64_tr_b16 v[112:113], v218 offset:28160
	v_add_f32_e32 v67, v92, v67
	v_add_f32_e32 v67, v93, v67
	v_add_f32_e32 v67, v94, v67
	v_add_f32_e32 v67, v95, v67
	v_cvt_pk_bf16_f32 v146, v90, v91
	v_cvt_pk_bf16_f32 v147, v92, v93
	s_waitcnt lgkmcnt(14)
	v_mfma_f32_32x32x16_bf16 v[130:145], v[182:185], v[154:157], v[130:145]
	ds_read_b64_tr_b16 v[90:91], v218 offset:31744
	ds_read_b64_tr_b16 v[92:93], v218 offset:32256
	v_add_f32_e32 v67, v96, v67
	v_add_f32_e32 v67, v97, v67
	v_cvt_pk_bf16_f32 v148, v94, v95
	v_cvt_pk_bf16_f32 v149, v96, v97
	v_mfma_f32_32x32x16_bf16 v[114:129], v[178:181], v[154:157], v[114:129]
	v_add_f32_e32 v198, v66, v67
	s_waitcnt lgkmcnt(14)
	v_mfma_f32_32x32x16_bf16 v[34:49], v[162:165], v[68:71], v[34:49]
	v_exp_f32_e32 v130, v130
	v_exp_f32_e32 v131, v131
	ds_read_b64_tr_b16 v[94:95], v218 offset:32768
	ds_read_b64_tr_b16 v[96:97], v218 offset:33280
	s_waitcnt lgkmcnt(14)
	v_mfma_f32_32x32x16_bf16 v[50:65], v[162:165], v[72:75], v[50:65]
	v_exp_f32_e32 v132, v132
	v_exp_f32_e32 v133, v133
	ds_read_b64_tr_b16 v[190:191], v218 offset:36864
	ds_read_b64_tr_b16 v[192:193], v218 offset:37376
	v_add_u32_e32 v66, s34, v238
	ds_read_b128 v[86:89], v66
	ds_read_b128 v[82:85], v66 offset:512
	s_waitcnt lgkmcnt(14)
	v_mfma_f32_32x32x16_bf16 v[34:49], v[158:161], v[76:79], v[34:49]
	v_exp_f32_e32 v134, v134
	v_exp_f32_e32 v135, v135
	ds_read_b64_tr_b16 v[194:195], v218 offset:33792
	ds_read_b64_tr_b16 v[196:197], v218 offset:34304
	ds_read_b128 v[182:185], v66 offset:2048
	ds_read_b128 v[78:81], v66 offset:2560
	v_mfma_f32_32x32x16_bf16 v[50:65], v[158:161], v[98:101], v[50:65]
	v_exp_f32_e32 v136, v136
	v_exp_f32_e32 v137, v137
	ds_read_b64_tr_b16 v[98:99], v218 offset:37888
	ds_read_b64_tr_b16 v[100:101], v218 offset:38400
	ds_read_b128 v[178:181], v66 offset:4096
	ds_read_b128 v[70:73], v66 offset:4608
	s_waitcnt lgkmcnt(14)
	v_mfma_f32_32x32x16_bf16 v[34:49], v[150:153], v[102:105], v[34:49]
	v_exp_f32_e32 v138, v138
	v_exp_f32_e32 v139, v139
	ds_read_b64_tr_b16 v[102:103], v218 offset:34816
	ds_read_b64_tr_b16 v[104:105], v218 offset:35328
	ds_read_b128 v[74:77], v66 offset:6144
	ds_read_b128 v[66:69], v66 offset:6656
	v_mfma_f32_32x32x16_bf16 v[50:65], v[150:153], v[106:109], v[50:65]
	v_exp_f32_e32 v140, v140
	v_exp_f32_e32 v141, v141
	ds_read_b64_tr_b16 v[106:107], v218 offset:38912
	ds_read_b64_tr_b16 v[108:109], v218 offset:39424
	v_mfma_f32_32x32x16_bf16 v[34:49], v[146:149], v[110:113], v[34:49]
	v_exp_f32_e32 v142, v142
	v_exp_f32_e32 v143, v143
	ds_read_b64_tr_b16 v[110:111], v218 offset:35840
	ds_read_b64_tr_b16 v[112:113], v218 offset:36352
	v_mfma_f32_32x32x16_bf16 v[50:65], v[146:149], v[90:93], v[50:65]
	v_exp_f32_e32 v144, v144
	v_exp_f32_e32 v145, v145
	ds_read_b64_tr_b16 v[90:91], v218 offset:39936
	ds_read_b64_tr_b16 v[92:93], v218 offset:40448
	s_waitcnt lgkmcnt(14)
	v_mfma_f32_32x32x16_bf16 v[2:17], v[162:165], v[94:97], v[2:17]
	v_exp_f32_e32 v114, v114
	v_exp_f32_e32 v115, v115
	v_lshl_add_u64 v[250:251], s[8:9], 0, v[216:217]
	s_add_i32 s32, s12, s96
	v_mfma_f32_32x32x16_bf16 v[18:33], v[162:165], v[190:193], v[18:33]
	v_exp_f32_e32 v116, v116
	v_exp_f32_e32 v117, v117
	v_lshl_add_u64 v[244:245], v[250:251], 0, s[22:23]
	s_mov_b32 m0, s32
	v_mfma_f32_32x32x16_bf16 v[2:17], v[158:161], v[194:197], v[2:17]
	v_exp_f32_e32 v118, v118
	v_exp_f32_e32 v119, v119
	global_load_lds_dwordx4 v[244:245], off
	v_lshl_add_u64 v[252:253], s[8:9], 0, v[214:215]
	s_lshl_b32 s32, s18, 1
	s_add_i32 s32, s32, s79
	s_waitcnt lgkmcnt(12)
	v_mfma_f32_32x32x16_bf16 v[18:33], v[158:161], v[98:101], v[18:33]
	v_exp_f32_e32 v120, v120
	v_exp_f32_e32 v121, v121
	v_lshl_add_u64 v[246:247], v[252:253], 0, s[24:25]
	s_mov_b32 m0, s32
	s_waitcnt lgkmcnt(8)
	v_mfma_f32_32x32x16_bf16 v[2:17], v[150:153], v[102:105], v[2:17]
	v_exp_f32_e32 v122, v122
	v_exp_f32_e32 v123, v123
	global_load_lds_dwordx4 v[246:247], off
	v_lshl_add_u64 v[248:249], v[252:253], 0, s[26:27]
	s_addk_i32 s32, 0x2000
	s_waitcnt lgkmcnt(4)
	v_mfma_f32_32x32x16_bf16 v[18:33], v[150:153], v[106:109], v[18:33]
	v_exp_f32_e32 v124, v124
	v_exp_f32_e32 v125, v125
	s_mov_b32 m0, s32
	s_waitcnt lgkmcnt(2)
	v_mfma_f32_32x32x16_bf16 v[2:17], v[146:149], v[110:113], v[2:17]
	v_exp_f32_e32 v126, v126
	v_exp_f32_e32 v127, v127
	global_load_lds_dwordx4 v[248:249], off
	s_waitcnt lgkmcnt(0)
	v_mfma_f32_32x32x16_bf16 v[18:33], v[146:149], v[90:93], v[18:33]
	v_exp_f32_e32 v128, v128
	v_exp_f32_e32 v129, v129
	s_add_i32 s4, s18, 0x2000
	s_cmpk_lg_i32 s18, 0x4000
	s_cselect_b32 s12, s4, 0
	s_waitcnt vmcnt(3) lgkmcnt(0)
	s_barrier
; #define WAIT_BAR(N) asm volatile("s_waitcnt vmcnt(" #N ") lgkmcnt(0)\n\ts_barrier":::"memory")
;   #define RESC() do{ if constexpr(!FIXED) if(resc){ asm volatile("s_waitcnt lgkmcnt(0)":::"memory"); \
;       _Pragma("unroll") for(int d_=0;d_<4;++d_) _Pragma("unroll") for(int r=0;r<16;++r)o[d_][r]*=wsf[crow(r,hi)]; } }while(0)
;   #define ROT() do{sl_prev=sl_cur;sl_cur=sl_next;sl_next=(sl_next==(NSLOT-1)*SLOTB)?0:sl_next+SLOTB;}while(0)
; template<int THRL,bool FIXED> __device__ __forceinline__ void attn_unit(int qb,const bf16*Q,const bf16*__restrict__ Kh,const bf16*__restrict__ Vh,bf16*O,const int*__restrict__ cid,char*shm,const int wid){
;     ...
;   int t=1;
;     ...
;   for(;t+5<NT;t+=2){
;     STEP(pB0,pB1,pA0,pA1,t,true,true,true);     WAIT_BAR(3); RESC(); ROT();
;     STEP(pA0,pA1,pB0,pB1,t+1,true,true,true);   WAIT_BAR(3); RESC(); ROT();
;   }
	v_lshl_add_u32 v218, s1, 1, v240
	ds_read_b64_tr_b16 v[190:191], v218 offset:24576
	ds_read_b64_tr_b16 v[192:193], v218 offset:25088
	v_mfma_f32_32x32x16_bf16 v[98:113], v[86:89], v[174:177], 0
	v_add_f32_e32 v90, v130, v131
	v_add_f32_e32 v90, v132, v90
	v_add_f32_e32 v90, v133, v90
	v_add_f32_e32 v90, v134, v90
	v_add_f32_e32 v90, v135, v90
	v_cvt_pk_bf16_f32 v162, v130, v131
	v_cvt_pk_bf16_f32 v163, v132, v133
	ds_read_b64_tr_b16 v[130:131], v218 offset:28672
	ds_read_b64_tr_b16 v[132:133], v218 offset:29184
	v_add_f32_e32 v86, v136, v90
	v_add_f32_e32 v86, v137, v86
	v_add_f32_e32 v86, v138, v86
	v_add_f32_e32 v146, v139, v86
	v_mfma_f32_32x32x16_bf16 v[82:97], v[82:85], v[174:177], 0
	v_cvt_pk_bf16_f32 v164, v134, v135
	v_cvt_pk_bf16_f32 v165, v136, v137
	ds_read_b64_tr_b16 v[134:135], v218 offset:25600
	ds_read_b64_tr_b16 v[136:137], v218 offset:26112
	v_mfma_f32_32x32x16_bf16 v[98:113], v[182:185], v[170:173], v[98:113]
	v_add_f32_e32 v146, v140, v146
	v_add_f32_e32 v146, v141, v146
	v_add_f32_e32 v146, v142, v146
	v_add_f32_e32 v146, v143, v146
	v_cvt_pk_bf16_f32 v158, v138, v139
	v_cvt_pk_bf16_f32 v159, v140, v141
	ds_read_b64_tr_b16 v[138:139], v218 offset:29696
	ds_read_b64_tr_b16 v[140:141], v218 offset:30208
	v_mfma_f32_32x32x16_bf16 v[82:97], v[78:81], v[170:173], v[82:97]
	v_add_f32_e32 v146, v144, v146
	v_add_f32_e32 v146, v145, v146
	v_add_f32_e32 v146, v114, v146
	v_add_f32_e32 v146, v115, v146
	v_cvt_pk_bf16_f32 v160, v142, v143
	v_cvt_pk_bf16_f32 v161, v144, v145
	ds_read_b64_tr_b16 v[78:79], v218 offset:26624
	ds_read_b64_tr_b16 v[80:81], v218 offset:27136
	v_mfma_f32_32x32x16_bf16 v[98:113], v[178:181], v[166:169], v[98:113]
	v_add_f32_e32 v142, v116, v146
	v_add_f32_e32 v142, v117, v142
	v_add_f32_e32 v142, v118, v142
	v_add_f32_e32 v142, v119, v142
	v_cvt_pk_bf16_f32 v150, v114, v115
	v_cvt_pk_bf16_f32 v151, v116, v117
	ds_read_b64_tr_b16 v[114:115], v218 offset:30720
	ds_read_b64_tr_b16 v[116:117], v218 offset:31232
	v_mfma_f32_32x32x16_bf16 v[82:97], v[70:73], v[166:169], v[82:97]
	v_add_f32_e32 v142, v120, v142
	v_add_f32_e32 v142, v121, v142
	v_add_f32_e32 v142, v122, v142
	v_add_f32_e32 v142, v123, v142
	v_cvt_pk_bf16_f32 v152, v118, v119
	v_cvt_pk_bf16_f32 v153, v120, v121
	ds_read_b64_tr_b16 v[70:71], v218 offset:27648
	ds_read_b64_tr_b16 v[72:73], v218 offset:28160
	v_mfma_f32_32x32x16_bf16 v[98:113], v[74:77], v[154:157], v[98:113]
	v_add_f32_e32 v118, v124, v142
	v_add_f32_e32 v118, v125, v118
	v_add_f32_e32 v118, v126, v118
	v_add_f32_e32 v118, v127, v118
	v_cvt_pk_bf16_f32 v146, v122, v123
	v_cvt_pk_bf16_f32 v147, v124, v125
	ds_read_b64_tr_b16 v[74:75], v218 offset:31744
	ds_read_b64_tr_b16 v[76:77], v218 offset:32256
	v_mfma_f32_32x32x16_bf16 v[82:97], v[66:69], v[154:157], v[82:97]
	v_add_f32_e32 v118, v128, v118
	v_add_f32_e32 v118, v129, v118
	v_cvt_pk_bf16_f32 v148, v126, v127
	v_cvt_pk_bf16_f32 v149, v128, v129
	v_add_f32_e32 v66, v198, v118
	s_add_i32 s10, s10, 2
	s_waitcnt lgkmcnt(14)
	v_mfma_f32_32x32x16_bf16 v[34:49], v[162:165], v[190:193], v[34:49]
	v_exp_f32_e32 v98, v98
	v_exp_f32_e32 v99, v99
	ds_read_b64_tr_b16 v[118:119], v218 offset:32768
	ds_read_b64_tr_b16 v[120:121], v218 offset:33280
	s_waitcnt lgkmcnt(14)
	v_mfma_f32_32x32x16_bf16 v[50:65], v[162:165], v[130:133], v[50:65]
	v_exp_f32_e32 v100, v100
	v_exp_f32_e32 v101, v101
	ds_read_b64_tr_b16 v[122:123], v218 offset:36864
	ds_read_b64_tr_b16 v[124:125], v218 offset:37376
	v_add_u32_e32 v67, s12, v238
	ds_read_b128 v[206:209], v67
	ds_read_b128 v[202:205], v67 offset:512
	s_waitcnt lgkmcnt(14)
	v_mfma_f32_32x32x16_bf16 v[34:49], v[158:161], v[134:137], v[34:49]
	v_exp_f32_e32 v102, v102
	v_exp_f32_e32 v103, v103
	ds_read_b64_tr_b16 v[126:127], v218 offset:33792
	ds_read_b64_tr_b16 v[128:129], v218 offset:34304
	ds_read_b128 v[198:201], v67 offset:2048
	ds_read_b128 v[194:197], v67 offset:2560
	v_mfma_f32_32x32x16_bf16 v[50:65], v[158:161], v[138:141], v[50:65]
	v_exp_f32_e32 v104, v104
	v_exp_f32_e32 v105, v105
	ds_read_b64_tr_b16 v[130:131], v218 offset:37888
	ds_read_b64_tr_b16 v[132:133], v218 offset:38400
	ds_read_b128 v[190:193], v67 offset:4096
	ds_read_b128 v[186:189], v67 offset:4608
	s_waitcnt lgkmcnt(14)
	v_mfma_f32_32x32x16_bf16 v[34:49], v[150:153], v[78:81], v[34:49]
	v_exp_f32_e32 v106, v106
	v_exp_f32_e32 v107, v107
	ds_read_b64_tr_b16 v[78:79], v218 offset:34816
	ds_read_b64_tr_b16 v[80:81], v218 offset:35328
	ds_read_b128 v[182:185], v67 offset:6144
	ds_read_b128 v[178:181], v67 offset:6656
	v_mfma_f32_32x32x16_bf16 v[50:65], v[150:153], v[114:117], v[50:65]
	v_exp_f32_e32 v108, v108
	v_exp_f32_e32 v109, v109
	ds_read_b64_tr_b16 v[114:115], v218 offset:38912
	ds_read_b64_tr_b16 v[116:117], v218 offset:39424
	v_mfma_f32_32x32x16_bf16 v[34:49], v[146:149], v[70:73], v[34:49]
	v_exp_f32_e32 v110, v110
	v_exp_f32_e32 v111, v111
	ds_read_b64_tr_b16 v[68:69], v218 offset:35840
	ds_read_b64_tr_b16 v[70:71], v218 offset:36352
	v_mfma_f32_32x32x16_bf16 v[50:65], v[146:149], v[74:77], v[50:65]
	v_exp_f32_e32 v112, v112
	v_exp_f32_e32 v113, v113
	ds_read_b64_tr_b16 v[72:73], v218 offset:39936
	ds_read_b64_tr_b16 v[74:75], v218 offset:40448
	s_waitcnt lgkmcnt(14)
	v_mfma_f32_32x32x16_bf16 v[2:17], v[162:165], v[118:121], v[2:17]
	v_exp_f32_e32 v82, v82
	v_exp_f32_e32 v83, v83
	s_add_i32 s32, s18, s96
	v_lshl_add_u64 v[244:245], v[250:251], 0, s[28:29]
	v_mfma_f32_32x32x16_bf16 v[18:33], v[162:165], v[122:125], v[18:33]
	v_exp_f32_e32 v84, v84
	v_exp_f32_e32 v85, v85
	s_mov_b32 m0, s32
	v_mfma_f32_32x32x16_bf16 v[2:17], v[158:161], v[126:129], v[2:17]
	v_exp_f32_e32 v86, v86
	v_exp_f32_e32 v87, v87
	global_load_lds_dwordx4 v[244:245], off
	s_lshl_b32 s32, s12, 1
	v_lshl_add_u64 v[246:247], v[252:253], 0, s[38:39]
	s_add_i32 s32, s32, s79
	s_waitcnt lgkmcnt(12)
	v_mfma_f32_32x32x16_bf16 v[18:33], v[158:161], v[130:133], v[18:33]
	v_exp_f32_e32 v88, v88
	v_exp_f32_e32 v89, v89
	s_mov_b32 m0, s32
	s_waitcnt lgkmcnt(8)
	v_mfma_f32_32x32x16_bf16 v[2:17], v[150:153], v[78:81], v[2:17]
	v_exp_f32_e32 v90, v90
	v_exp_f32_e32 v91, v91
	global_load_lds_dwordx4 v[246:247], off
	v_lshl_add_u64 v[248:249], v[252:253], 0, s[40:41]
	s_addk_i32 s32, 0x2000
	s_waitcnt lgkmcnt(4)
	v_mfma_f32_32x32x16_bf16 v[18:33], v[150:153], v[114:117], v[18:33]
	v_exp_f32_e32 v92, v92
	v_exp_f32_e32 v93, v93
	s_mov_b32 m0, s32
	s_waitcnt lgkmcnt(2)
	v_mfma_f32_32x32x16_bf16 v[2:17], v[146:149], v[68:71], v[2:17]
	v_exp_f32_e32 v94, v94
	v_exp_f32_e32 v95, v95
	global_load_lds_dwordx4 v[248:249], off
	s_waitcnt lgkmcnt(0)
	v_mfma_f32_32x32x16_bf16 v[18:33], v[146:149], v[72:75], v[18:33]
	v_exp_f32_e32 v96, v96
	v_exp_f32_e32 v97, v97
	s_add_i32 s1, s12, 0x2000
	s_cmpk_lg_i32 s12, 0x4000
	s_cselect_b32 s18, s1, 0
	v_lshl_add_u64 v[214:215], v[214:215], 0, s[16:17]
	v_lshl_add_u64 v[216:217], v[216:217], 0, s[16:17]
	s_mov_b32 s4, s34
	s_waitcnt vmcnt(3) lgkmcnt(0)
	s_barrier
	s_cmp_ge_i32 s10, s0
	s_cbranch_scc0 .LBB0_1062
	s_add_i32 s0, s10, 1
	s_cmp_lt_i32 s0, s13
	v_lshlrev_b32_e32 v67, 4, v234
	s_cbranch_scc1 .LBB0_1069
